# P0 f32->bf16 conversion loops (p per layer, x at layer 0) unrolled by two with the second element's loads issued before the first is converted; on top of v56
# baseline (speedup 1.0000x reference)
; DI u32x4 pack8(f32x4 a, f32x4 b) { u32x4 w; w.x = pk2(a[0], a[1]); w.y = pk2(a[2], a[3]); w.z = pk2(b[0], b[1]); w.w = pk2(b[2], b[3]); return w; }
; DI void phase_p0(LAS unsigned char* lds, const Ctx& c, int l) {
;     ...
;     const size_t gt = (size_t)blockIdx.x * NT + tid, GT = (size_t)gridDim.x * NT;
;     {
;         const f32x4* src = (const f32x4*)(c.p + (size_t)l * T * 256); u32x4* dst = (u32x4*)(ws + WS_PB);
;         for (size_t i = gt; i < (size_t)T * 256 / 8; i += GT) dst[i] = pack8(src[2 * i], src[2 * i + 1]);
;     }
.LBB0_721:
	global_load_dwordx4 v[12:15], v[8:9], off offset:-16
	global_load_dwordx4 v[16:19], v[8:9], off
	v_lshl_add_u64 v[10:11], v[10:11], 0, s[28:29]
	v_cmp_lt_u64_e64 s[40:41], s[10:11], v[10:11]
	v_lshl_add_u64 v[8:9], v[8:9], 0, s[38:39]
	s_mov_b64 s[98:99], exec
	s_andn2_b64 exec, exec, s[40:41]
	global_load_dwordx4 v[100:103], v[8:9], off offset:-16
	global_load_dwordx4 v[104:107], v[8:9], off
	s_mov_b64 exec, s[98:99]
	v_lshl_add_u64 v[10:11], v[10:11], 0, s[28:29]
	v_cmp_lt_u64_e64 s[100:101], s[10:11], v[10:11]
	v_lshl_add_u64 v[8:9], v[8:9], 0, s[38:39]
	s_or_b64 s[100:101], s[100:101], s[40:41]
	s_or_b64 s[6:7], s[100:101], s[6:7]
	s_waitcnt vmcnt(3)
	v_cvt_pk_bf16_f32 v12, v12, v13
	v_cvt_pk_bf16_f32 v13, v14, v15
	s_waitcnt vmcnt(2)
	v_cvt_pk_bf16_f32 v14, v16, v17
	v_cvt_pk_bf16_f32 v15, v18, v19
	global_store_dwordx4 v[6:7], v[12:15], off
	v_lshl_add_u64 v[6:7], v[6:7], 0, s[34:35]
	s_andn2_b64 exec, exec, s[40:41]
	s_waitcnt vmcnt(1)
	v_cvt_pk_bf16_f32 v100, v100, v101
	v_cvt_pk_bf16_f32 v101, v102, v103
	v_cvt_pk_bf16_f32 v102, v104, v105
	v_cvt_pk_bf16_f32 v103, v106, v107
	global_store_dwordx4 v[6:7], v[100:103], off
	s_mov_b64 exec, s[98:99]
	v_lshl_add_u64 v[6:7], v[6:7], 0, s[34:35]
	s_andn2_b64 exec, exec, s[6:7]
	s_cbranch_execnz .LBB0_721

; DI u32x4 pack8(f32x4 a, f32x4 b) { u32x4 w; w.x = pk2(a[0], a[1]); w.y = pk2(a[2], a[3]); w.z = pk2(b[0], b[1]); w.w = pk2(b[2], b[3]); return w; }
; DI void phase_p0(LAS unsigned char* lds, const Ctx& c, int l) {
;     ...
;         const f32x4* src = (const f32x4*)c.x; u32x4* dst = (u32x4*)(ws + WS_XB);
;         for (size_t i = gt; i < (size_t)T * DM / 8; i += GT) dst[i] = pack8(src[2 * i], src[2 * i + 1]);
.LBB0_728:
	global_load_dwordx4 v[12:15], v[8:9], off offset:-16
	global_load_dwordx4 v[16:19], v[8:9], off
	v_lshl_add_u64 v[10:11], v[10:11], 0, s[28:29]
	s_mov_b64 s[8:9], 0x3fffff
	v_cmp_lt_u64_e64 s[40:41], s[8:9], v[10:11]
	v_lshl_add_u64 v[8:9], v[8:9], 0, s[38:39]
	s_mov_b64 s[98:99], exec
	s_andn2_b64 exec, exec, s[40:41]
	global_load_dwordx4 v[100:103], v[8:9], off offset:-16
	global_load_dwordx4 v[104:107], v[8:9], off
	s_mov_b64 exec, s[98:99]
	v_lshl_add_u64 v[10:11], v[10:11], 0, s[28:29]
	v_cmp_lt_u64_e64 s[100:101], s[8:9], v[10:11]
	v_lshl_add_u64 v[8:9], v[8:9], 0, s[38:39]
	s_or_b64 s[100:101], s[100:101], s[40:41]
	s_or_b64 s[6:7], s[100:101], s[6:7]
	s_waitcnt vmcnt(3)
	v_cvt_pk_bf16_f32 v12, v12, v13
	v_cvt_pk_bf16_f32 v13, v14, v15
	s_waitcnt vmcnt(2)
	v_cvt_pk_bf16_f32 v14, v16, v17
	v_cvt_pk_bf16_f32 v15, v18, v19
	global_store_dwordx4 v[6:7], v[12:15], off
	v_lshl_add_u64 v[6:7], v[6:7], 0, s[34:35]
	s_andn2_b64 exec, exec, s[40:41]
	s_waitcnt vmcnt(1)
	v_cvt_pk_bf16_f32 v100, v100, v101
	v_cvt_pk_bf16_f32 v101, v102, v103
	v_cvt_pk_bf16_f32 v102, v104, v105
	v_cvt_pk_bf16_f32 v103, v106, v107
	global_store_dwordx4 v[6:7], v[100:103], off
	s_mov_b64 exec, s[98:99]
	v_lshl_add_u64 v[6:7], v[6:7], 0, s[34:35]
	s_andn2_b64 exec, exec, s[6:7]
	s_cbranch_execnz .LBB0_728

; template <int KP> __global__ void __launch_bounds__(NT, 2) fwd_kernel(Args args) {
	.amdhsa_kernel _Z10fwd_kernelILin1EEv4Args
		.amdhsa_group_segment_fixed_size 0
		.amdhsa_private_segment_fixed_size 0
		.amdhsa_kernarg_size 448
		.amdhsa_user_sgpr_count 2
		.amdhsa_user_sgpr_dispatch_ptr 0
		.amdhsa_user_sgpr_queue_ptr 0
		.amdhsa_user_sgpr_kernarg_segment_ptr 1
		.amdhsa_user_sgpr_dispatch_id 0
		.amdhsa_user_sgpr_kernarg_preload_length 0
		.amdhsa_user_sgpr_kernarg_preload_offset 0
		.amdhsa_user_sgpr_private_segment_size 0
		.amdhsa_uses_dynamic_stack 0
		.amdhsa_enable_private_segment 0
		.amdhsa_system_sgpr_workgroup_id_x 1
		.amdhsa_system_sgpr_workgroup_id_y 0
		.amdhsa_system_sgpr_workgroup_id_z 0
		.amdhsa_system_sgpr_workgroup_info 0
		.amdhsa_system_vgpr_workitem_id 2
		.amdhsa_next_free_vgpr 256
		.amdhsa_next_free_sgpr 102
		.amdhsa_accum_offset 256
		.amdhsa_reserve_vcc 1
		.amdhsa_float_round_mode_32 0
		.amdhsa_float_round_mode_16_64 0
		.amdhsa_float_denorm_mode_32 3
		.amdhsa_float_denorm_mode_16_64 3
		.amdhsa_dx10_clamp 1
		.amdhsa_ieee_mode 1
		.amdhsa_fp16_overflow 0
		.amdhsa_tg_split 0
		.amdhsa_exception_fp_ieee_invalid_op 0
		.amdhsa_exception_fp_denorm_src 0
		.amdhsa_exception_fp_ieee_div_zero 0
		.amdhsa_exception_fp_ieee_overflow 0
		.amdhsa_exception_fp_ieee_underflow 0
		.amdhsa_exception_fp_ieee_inexact 0
		.amdhsa_exception_int_div_zero 0
	.end_amdhsa_kernel

; template <int KP> __global__ void __launch_bounds__(NT, 2) fwd_kernel(Args args) {
amdhsa.kernels:
  - .agpr_count:     0
    .args:
      - .offset:         0
        .size:           192
        .value_kind:     by_value
      - .offset:         192
        .size:           4
        .value_kind:     hidden_block_count_x
      - .offset:         196
        .size:           4
        .value_kind:     hidden_block_count_y
      - .offset:         200
        .size:           4
        .value_kind:     hidden_block_count_z
      - .offset:         204
        .size:           2
        .value_kind:     hidden_group_size_x
      - .offset:         206
        .size:           2
        .value_kind:     hidden_group_size_y
      - .offset:         208
        .size:           2
        .value_kind:     hidden_group_size_z
      - .offset:         210
        .size:           2
        .value_kind:     hidden_remainder_x
      - .offset:         212
        .size:           2
        .value_kind:     hidden_remainder_y
      - .offset:         214
        .size:           2
        .value_kind:     hidden_remainder_z
      - .offset:         232
        .size:           8
        .value_kind:     hidden_global_offset_x
      - .offset:         240
        .size:           8
        .value_kind:     hidden_global_offset_y
      - .offset:         248
        .size:           8
        .value_kind:     hidden_global_offset_z
      - .offset:         256
        .size:           2
        .value_kind:     hidden_grid_dims
      - .offset:         280
        .size:           8
        .value_kind:     hidden_multigrid_sync_arg
      - .offset:         312
        .size:           4
        .value_kind:     hidden_dynamic_lds_size
    .group_segment_fixed_size: 0
    .kernarg_segment_align: 8
    .kernarg_segment_size: 448
    .language:       OpenCL C
    .language_version:
      - 2
      - 0
    .max_flat_workgroup_size: 512
    .name:           _Z10fwd_kernelILin1EEv4Args
    .private_segment_fixed_size: 0
    .sgpr_count:     108
    .sgpr_spill_count: 198
    .symbol:         _Z10fwd_kernelILin1EEv4Args.kd
    .uniform_work_group_size: 1
    .uses_dynamic_stack: false
    .vgpr_count:     256
    .vgpr_spill_count: 0
    .wavefront_size: 64
